# grid barrier: XCD leaders no longer post the unused per-XCD generation word nor wait for their release atomic before leaving the barrier
# speedup vs baseline: 1.0149x; 1.0036x over previous
; __device__ __forceinline__ unsigned xb_ld(unsigned* p)              { return __hip_atomic_load(p, __ATOMIC_RELAXED, __HIP_MEMORY_SCOPE_AGENT); }
; __device__ __forceinline__ unsigned xb_add(unsigned* p, unsigned v) { return __hip_atomic_fetch_add(p, v, __ATOMIC_RELAXED, __HIP_MEMORY_SCOPE_AGENT); }
; #define XB_SPIN(cond, bar) do { unsigned _sp = 0; while (cond) { __builtin_amdgcn_s_sleep(1); \
;     if ((++_sp & 255u) == 0u) { if (xb_ld(&(bar)[XB_TMO])) break; if (_sp > XB_SPIN_CAP) { atomicAdd(&(bar)[XB_TMO], 1u); break; } } } } while (0)
; #define GSYNC() xcd_barrier(xb)
; __device__ __forceinline__ void xcd_barrier(const XcdBarrier& b) {
;     ...
;         const unsigned old = xb_add(&bar[XB_XSUB(b.x)], 1u);
;         const unsigned gen = old / nloc;
;         if (old + 1u == (gen + 1u) * nloc) {
;             __builtin_amdgcn_fence(__ATOMIC_RELEASE, "agent");
;             asm volatile("s_waitcnt vmcnt(0)" ::: "memory");
;             const unsigned og = xb_add(&bar[XB_TOP], 1u);
;             const unsigned tg = og / nx;
;             if (og + 1u == (tg + 1u) * nx) xb_add(&bar[XB_TOPGEN], 1u);
;             else XB_SPIN(xb_ld(&bar[XB_TOPGEN]) == tg, bar);
;             __builtin_amdgcn_fence(__ATOMIC_ACQUIRE, "agent");
;             xb_add(&bar[XB_XGEN(b.x)], 1u);
;             asm volatile("s_waitcnt vmcnt(0)" ::: "memory");
; __global__ void __launch_bounds__(512, 2) fwd_megakernel(Params p) {
;     ...
;     GSYNC();
;     if (blockIdx.x == 0 && threadIdx.x == 0) __hip_atomic_store(barw + 16384 - 64, 0u, __ATOMIC_RELAXED, __HIP_MEMORY_SCOPE_AGENT);
.LBB0_114:
.LBB0_115:
	s_or_b64 exec, exec, s[0:1]
	s_waitcnt lgkmcnt(0)
	v_or_b32_e32 v0, s86, v152
	v_cmp_eq_u32_e32 vcc, 0, v0
	s_barrier
	s_and_saveexec_b64 s[0:1], vcc
	s_cbranch_execz .LBB0_117
	v_mov_b32_e32 v0, 0
	global_store_dword v0, v0, s[26:27] sc1

; __device__ __forceinline__ unsigned xb_ld(unsigned* p)              { return __hip_atomic_load(p, __ATOMIC_RELAXED, __HIP_MEMORY_SCOPE_AGENT); }
; __device__ __forceinline__ unsigned xb_add(unsigned* p, unsigned v) { return __hip_atomic_fetch_add(p, v, __ATOMIC_RELAXED, __HIP_MEMORY_SCOPE_AGENT); }
; #define XB_SPIN(cond, bar) do { unsigned _sp = 0; while (cond) { __builtin_amdgcn_s_sleep(1); \
;     if ((++_sp & 255u) == 0u) { if (xb_ld(&(bar)[XB_TMO])) break; if (_sp > XB_SPIN_CAP) { atomicAdd(&(bar)[XB_TMO], 1u); break; } } } } while (0)
; #define GSYNC() xcd_barrier(xb)
;     __host__ __device__ bool next(int i, Unit& u) const {
;         const long L = (long)i * G + c; if (L >= nwg) return false;
;         int wgid = (int)L; { const int q = nwg / NXCD, r = nwg % NXCD, xcd = wgid % NXCD, off = wgid / NXCD; wgid = (xcd < r ? xcd * (q + 1) : r * (q + 1) + (xcd - r) * q) + off; }
;         const int nig = WGM * nN, gid = wgid / nig, fm = gid * WGM, gsz = (nM - fm) < WGM ? (nM - fm) : WGM;
;         u.pm = fm + ((wgid % nig) % gsz); u.pn = (wgid % nig) / gsz; return true;
; __device__ __forceinline__ void xcd_barrier(const XcdBarrier& b) {
;     ...
;         const unsigned old = xb_add(&bar[XB_XSUB(b.x)], 1u);
;         const unsigned gen = old / nloc;
;         if (old + 1u == (gen + 1u) * nloc) {
;             __builtin_amdgcn_fence(__ATOMIC_RELEASE, "agent");
;             asm volatile("s_waitcnt vmcnt(0)" ::: "memory");
;             const unsigned og = xb_add(&bar[XB_TOP], 1u);
;             const unsigned tg = og / nx;
;             if (og + 1u == (tg + 1u) * nx) xb_add(&bar[XB_TOPGEN], 1u);
;             else XB_SPIN(xb_ld(&bar[XB_TOPGEN]) == tg, bar);
;             __builtin_amdgcn_fence(__ATOMIC_ACQUIRE, "agent");
;             xb_add(&bar[XB_XGEN(b.x)], 1u);
;             asm volatile("s_waitcnt vmcnt(0)" ::: "memory");
; __global__ void __launch_bounds__(512, 2) fwd_megakernel(Params p) {
;     ...
;     GSYNC();
;     { pg8::Gemm g{HB, (const bf16*)(ws + WS_WD1), S, DM, DFF}; pg8::StaticOrder so; so.init(S, DM, G, (int)blockIdx.x);
;       pg8::EpiResid<true> E{nullptr, XB, SS1, 0.5f}; pg8::gemm_phase<pg8::EpiResid<true>, pg8::StaticOrder, true, true>(ldsl, g, so, E); }
.LBB0_348:
.LBB0_349:
	s_or_b64 exec, exec, s[0:1]
	s_cmpk_lt_i32 s86, 0x100
	v_lshrrev_b32_e32 v175, 2, v152
	s_cselect_b64 s[0:1], -1, 0
	s_cmpk_gt_i32 s86, 0xff
	v_readfirstlane_b32 s8, v152
	s_waitcnt lgkmcnt(0)
	s_barrier
	s_cbranch_scc1 .LBB0_355
	s_ashr_i32 s2, s86, 31
	s_lshr_b32 s2, s2, 29
	s_add_i32 s2, s86, s2
	s_and_b32 s3, s2, -8
	s_sub_i32 s3, s86, s3
	s_cmp_gt_i32 s3, -1
	s_cbranch_scc0 .LBB0_352
	s_lshl_b32 s6, s3, 5
	s_cbranch_execz .LBB0_353
	s_branch .LBB0_354

; __device__ __forceinline__ unsigned xb_ld(unsigned* p)              { return __hip_atomic_load(p, __ATOMIC_RELAXED, __HIP_MEMORY_SCOPE_AGENT); }
; __device__ __forceinline__ unsigned xb_add(unsigned* p, unsigned v) { return __hip_atomic_fetch_add(p, v, __ATOMIC_RELAXED, __HIP_MEMORY_SCOPE_AGENT); }
; #define XB_SPIN(cond, bar) do { unsigned _sp = 0; while (cond) { __builtin_amdgcn_s_sleep(1); \
;     if ((++_sp & 255u) == 0u) { if (xb_ld(&(bar)[XB_TMO])) break; if (_sp > XB_SPIN_CAP) { atomicAdd(&(bar)[XB_TMO], 1u); break; } } } } while (0)
; #define GSYNC() xcd_barrier(xb)
;     __host__ __device__ bool next(int i, Unit& u) const {
;         const long L = (long)i * G + c; if (L >= nwg) return false;
;         int wgid = (int)L; { const int q = nwg / NXCD, r = nwg % NXCD, xcd = wgid % NXCD, off = wgid / NXCD; wgid = (xcd < r ? xcd * (q + 1) : r * (q + 1) + (xcd - r) * q) + off; }
;         const int nig = WGM * nN, gid = wgid / nig, fm = gid * WGM, gsz = (nM - fm) < WGM ? (nM - fm) : WGM;
;         u.pm = fm + ((wgid % nig) % gsz); u.pn = (wgid % nig) / gsz; return true;
; __device__ __forceinline__ void xcd_barrier(const XcdBarrier& b) {
;     ...
;         const unsigned old = xb_add(&bar[XB_XSUB(b.x)], 1u);
;         const unsigned gen = old / nloc;
;         if (old + 1u == (gen + 1u) * nloc) {
;             __builtin_amdgcn_fence(__ATOMIC_RELEASE, "agent");
;             asm volatile("s_waitcnt vmcnt(0)" ::: "memory");
;             const unsigned og = xb_add(&bar[XB_TOP], 1u);
;             const unsigned tg = og / nx;
;             if (og + 1u == (tg + 1u) * nx) xb_add(&bar[XB_TOPGEN], 1u);
;             else XB_SPIN(xb_ld(&bar[XB_TOPGEN]) == tg, bar);
;             __builtin_amdgcn_fence(__ATOMIC_ACQUIRE, "agent");
;             xb_add(&bar[XB_XGEN(b.x)], 1u);
;             asm volatile("s_waitcnt vmcnt(0)" ::: "memory");
; __global__ void __launch_bounds__(512, 2) fwd_megakernel(Params p) {
;     ...
;     GSYNC();
;     { pg8::Gemm g{XB, (const bf16*)(ws + WS_WIN), S, NPROJ, DM}; pg8::StaticOrder so; so.init(S, NPROJ, G, (int)blockIdx.x);
;       const int pm0 = fill_rtab(so, SS1, rtab); pg8::EpiProj E{HB, NPROJ, SS1, (float*)(ws + WS_GATES), p.bg, 10, rtab, pm0}; pg8::gemm_phase<pg8::EpiProj, pg8::StaticOrder, true, true>(ldsl, g, so, E); }
.LBB0_446:
.LBB0_447:
	s_or_b64 exec, exec, s[0:1]
	s_cmpk_lt_i32 s86, 0x2c0
	v_lshrrev_b32_e32 v165, 4, v152
	s_cselect_b64 s[4:5], -1, 0
	s_cmpk_gt_i32 s86, 0x2bf
	s_waitcnt lgkmcnt(0)
	s_barrier
	s_cbranch_scc1 .LBB0_449
	s_ashr_i32 s0, s86, 31
	s_lshr_b32 s0, s0, 29
	s_add_i32 s0, s86, s0
	s_ashr_i32 s1, s0, 3
	s_and_b32 s0, s0, -8
	s_sub_i32 s0, s86, s0
	s_cmp_lt_i32 s0, 0
	s_movk_i32 s2, 0x59
	s_cselect_b32 s2, s2, 0x58
	s_mul_i32 s0, s0, s2
	s_add_i32 s0, s0, s1
	s_mul_hi_i32 s1, s0, 0x2e8ba2e9
	s_lshr_b32 s2, s1, 31
	s_ashr_i32 s1, s1, 4
	s_add_i32 s1, s1, s2
	s_lshl_b32 s2, s1, 3
	s_mulk_i32 s1, 0x58
	s_sub_i32 s0, s0, s1
	s_bfe_i32 s1, s0, 0x80000
	s_bfe_u32 s1, s1, 0x3000c
	s_add_i32 s1, s0, s1
	s_and_b32 s1, s1, 0xf8
	s_sub_i32 s0, s0, s1
	s_sext_i32_i8 s0, s0
	s_add_i32 s3, s2, s0

; __device__ __forceinline__ unsigned xb_ld(unsigned* p)              { return __hip_atomic_load(p, __ATOMIC_RELAXED, __HIP_MEMORY_SCOPE_AGENT); }
; __device__ __forceinline__ unsigned xb_add(unsigned* p, unsigned v) { return __hip_atomic_fetch_add(p, v, __ATOMIC_RELAXED, __HIP_MEMORY_SCOPE_AGENT); }
; #define GSYNC() xcd_barrier(xb)
; __device__ __forceinline__ void m1_phase(const Params& p, unsigned char* ldsg, int G) {
;     const int tid = threadIdx.x, lane = tid & 63, wave = __builtin_amdgcn_readfirstlane(tid >> 6), fr = lane & 15, fq = lane >> 4;
;     const int half = wave >> 2, hw = wave & 3, htid = tid & 255;
;     unsigned char* ws = p.ws;
;     const bf16* PROJ = (const bf16*)(ws + WS_HB); const float* GATES = (const float*)(ws + WS_GATES);
;     bf16* DCB = (bf16*)p.out; bf16* QKC = (bf16*)((unsigned char*)p.out + 32 * MiB); float* DN = (float*)(ws + WS_DN); float* GARR = (float*)(ws + WS_SC); float* AMAXARR = GARR + 1024;
;     bf16* KT = (bf16*)(ldsg + half * 40960); bf16* VT = KT + 128 * TP; float* sW = (float*)(ldsg + half * 40960 + 36864);
;     for (int r = blockIdx.x; r < NCH * NH / 2; r += G) {
; __device__ __forceinline__ void xcd_barrier(const XcdBarrier& b) {
;     ...
;         const unsigned old = xb_add(&bar[XB_XSUB(b.x)], 1u);
;         const unsigned gen = old / nloc;
;         if (old + 1u == (gen + 1u) * nloc) {
;             __builtin_amdgcn_fence(__ATOMIC_RELEASE, "agent");
;             asm volatile("s_waitcnt vmcnt(0)" ::: "memory");
;             const unsigned og = xb_add(&bar[XB_TOP], 1u);
;             const unsigned tg = og / nx;
;             if (og + 1u == (tg + 1u) * nx) xb_add(&bar[XB_TOPGEN], 1u);
;             else XB_SPIN(xb_ld(&bar[XB_TOPGEN]) == tg, bar);
;             __builtin_amdgcn_fence(__ATOMIC_ACQUIRE, "agent");
;             xb_add(&bar[XB_XGEN(b.x)], 1u);
;             asm volatile("s_waitcnt vmcnt(0)" ::: "memory");
; __global__ void __launch_bounds__(512, 2) fwd_megakernel(Params p) {
;     ...
;     GSYNC();
;     m1_phase(p, lds, G);
;     GSYNC();
;     m2_phase(p, lds, G);
;     GSYNC();
;     m3_phase(p, lds, G);
;     GSYNC();
;     { pg8::Gemm g{MIX, (const bf16*)(ws + WS_WOUT), S, DM, DM}; pg8::StaticOrder so; so.init(S, DM, G, (int)blockIdx.x);
.LBB0_607:
.LBB0_608:
	s_or_b64 exec, exec, s[0:1]
	s_add_u32 s56, s70, 0x2000000
	s_addc_u32 s57, s71, 0
	s_add_u32 s34, s72, 0x500000
	s_addc_u32 s35, s73, 0
	s_add_u32 s36, s72, 0x501000
	v_lshrrev_b32_e32 v159, 4, v153
	s_addc_u32 s37, s73, 0
	v_readfirstlane_b32 s0, v240
	s_cmpk_gt_i32 s86, 0x1ff
	v_cmp_gt_u32_e64 s[8:9], 2, v153
	v_cmp_gt_u32_e64 s[10:11], 4, v153
	v_cmp_gt_u32_e64 s[12:13], 8, v153
	v_cmp_gt_u32_e64 s[14:15], 32, v153
	v_lshlrev_b32_e32 v92, 3, v159
	v_lshlrev_b32_e32 v167, 8, v152
	v_and_b32_e32 v157, 8, v152
	s_waitcnt lgkmcnt(0)
	s_barrier
	s_cbranch_scc1 .LBB0_648
	s_ashr_i32 s2, s0, 2
	v_and_b32_e32 v64, 0x78, v230
	s_mul_i32 s1, s2, 0xa000
	v_mov_b32_e32 v67, 0
	v_lshlrev_b32_e32 v66, 1, v64
	v_and_b32_e32 v0, 56, v230
	s_add_i32 s1, s1, 0
	v_and_b32_e32 v2, 0xff, v152
	v_lshl_add_u64 v[68:69], s[56:57], 0, v[66:67]
	v_bitop3_b32 v0, v175, v0, 60 bitop3:0x6c
	v_and_b32_e32 v66, 0x100, v167
	s_and_b32 s3, s0, 3
	v_and_b32_e32 v118, 60, v175
	v_lshl_add_u32 v4, v0, 1, s1
	v_lshl_add_u64 v[0:1], s[70:71], 0, v[66:67]
	v_mov_b32_e32 v93, v67
	s_movk_i32 s0, 0x80
	v_lshlrev_b32_e32 v66, 2, v2
	v_mov_b32_e32 v3, s1
	v_lshl_add_u32 v65, v153, 2, s1
	v_lshl_add_u32 v120, v118, 2, s1
	v_lshl_or_b32 v5, s3, 5, v234
	v_lshl_add_u64 v[70:71], v[0:1], 0, v[92:93]
	v_cmp_gt_u32_e64 s[20:21], s0, v2
	s_movk_i32 s6, 0x90
	v_lshl_add_u64 v[0:1], s[72:73], 0, v[66:67]
	s_mov_b64 s[0:1], 0x480000
	v_mad_u32_u24 v93, v2, s6, v3
	v_lshl_add_u64 v[72:73], v[0:1], 0, s[0:1]
	v_mad_u32_u24 v1, v5, s6, v3
	v_bitop3_b32 v2, v5, v92, 40 bitop3:0x6c
	v_lshl_add_u32 v121, v2, 1, v1
	v_or_b32_e32 v2, 32, v92
	v_bitop3_b32 v7, v5, v2, 40 bitop3:0x6c
	v_or_b32_e32 v5, 16, v5
	v_lshl_add_u32 v122, v7, 1, v1
	v_add_u32_e32 v1, 0x900, v1
	v_bitop3_b32 v7, v5, v92, 56 bitop3:0x6c
	v_bitop3_b32 v2, v5, v2, 56 bitop3:0x6c
	v_lshl_add_u32 v123, v7, 1, v1
	v_lshl_add_u32 v124, v2, 1, v1
	v_mad_u32_u24 v1, v234, s6, v3
	v_bitop3_b32 v2, v92, v152, 8 bitop3:0x78
	v_lshlrev_b32_e32 v6, 7, v152
	v_lshl_add_u32 v125, v2, 1, v1
	v_bitop3_b32 v2, v92, v157, 32 bitop3:0x36
	v_lshl_add_u32 v126, v2, 1, v1
	v_and_b32_e32 v2, 0x700, v6
	v_lshl_or_b32 v127, s3, 12, v2
	v_or_b32_e32 v2, 16, v234
	v_bitop3_b32 v3, v234, 24, 16 bitop3:0xc8
	v_bitop3_b32 v2, v92, v2, 24 bitop3:0x78
	v_bitop3_b32 v3, v92, v3, 32 bitop3:0x36
	v_add_u32_e32 v5, 0x900, v1
	v_lshlrev_b32_e32 v2, 1, v2
	v_lshlrev_b32_e32 v3, 1, v3
	v_add_u32_e32 v129, v5, v2
	v_add_u32_e32 v130, v5, v3
	v_or_b32_e32 v5, 32, v234
	v_bitop3_b32 v6, v234, 40, 32 bitop3:0xc8
	v_bitop3_b32 v5, v92, v5, 40 bitop3:0x78
	v_bitop3_b32 v6, v92, v6, 32 bitop3:0x36
	v_add_u32_e32 v7, 0x1200, v1
	v_lshlrev_b32_e32 v5, 1, v5
	v_lshlrev_b32_e32 v6, 1, v6
	v_add_u32_e32 v131, v7, v5
	v_add_u32_e32 v132, v7, v6
	v_or_b32_e32 v7, 48, v234
	v_bitop3_b32 v8, v234, 56, 48 bitop3:0xc8
	v_bitop3_b32 v7, v92, v7, 56 bitop3:0x78
	v_bitop3_b32 v8, v92, v8, 32 bitop3:0x36
	v_mul_u32_u24_e32 v0, 0x90, v64
	v_add_u32_e32 v9, 0x1b00, v1
	v_lshlrev_b32_e32 v7, 1, v7
	v_lshlrev_b32_e32 v8, 1, v8
	v_add_u32_e32 v133, v9, v7
	v_add_u32_e32 v134, v9, v8
	v_add_u32_e32 v9, 0x2d00, v1
	v_add_u32_e32 v142, v4, v0
	v_mbcnt_lo_u32_b32 v0, -1, 0
	s_cmp_eq_u32 s3, 0
	v_add_u32_e32 v135, v9, v2
	v_add_u32_e32 v2, 0x3600, v1
	v_add_u32_e32 v1, 0x3f00, v1
	v_mbcnt_hi_u32_b32 v144, -1, v0
	v_bfrev_b32_e32 v0, 0.5
	s_cselect_b64 s[4:5], -1, 0
	v_cmp_eq_u32_e64 s[16:17], 0, v153
	v_cmp_gt_u32_e64 s[18:19], 16, v153
	v_or_b32_e32 v119, 0x200, v64
	v_or_b32_e32 v128, 0x800, v127
	v_add_u32_e32 v136, v9, v3
	v_add_u32_e32 v137, v2, v5
	v_add_u32_e32 v138, v2, v6
	v_add_u32_e32 v139, v1, v7
	v_add_u32_e32 v140, v1, v8
	s_mov_b32 s3, 0xbfb8aa3b
	v_mov_b32_e32 v141, 0x3ecc95a3
	s_mov_b32 s33, 0x3f317218
	s_mov_b32 s43, 0x33800000
	s_mov_b32 s46, 0x3fb8aa3b
	s_mov_b32 s47, 0xc2ce8ed0
	s_mov_b32 s62, 0x42b17218
	s_movk_i32 s63, 0x1600
	s_mov_b32 s64, 0xffff0000
	s_mov_b64 s[6:7], 0x1000
	s_mov_b64 s[38:39], 0x2000
	s_movk_i32 s65, 0x2000
	s_mov_b64 s[40:41], 0x3000
	s_movk_i32 s80, 0x3000
	s_movk_i32 s81, 0x7fff
	s_mov_b32 s42, 0x3db504f3
	v_lshlrev_b32_e32 v66, 1, v64
	v_mov_b32_e32 v143, 0x7f800000
	v_lshl_or_b32 v145, v144, 2, v0
	v_mov_b32_e32 v146, 1
	s_mov_b32 s82, s86
	s_branch .LBB0_611

; __device__ __forceinline__ unsigned xb_ld(unsigned* p)              { return __hip_atomic_load(p, __ATOMIC_RELAXED, __HIP_MEMORY_SCOPE_AGENT); }
; __device__ __forceinline__ unsigned xb_add(unsigned* p, unsigned v) { return __hip_atomic_fetch_add(p, v, __ATOMIC_RELAXED, __HIP_MEMORY_SCOPE_AGENT); }
; #define XB_SPIN(cond, bar) do { unsigned _sp = 0; while (cond) { __builtin_amdgcn_s_sleep(1); \
;     if ((++_sp & 255u) == 0u) { if (xb_ld(&(bar)[XB_TMO])) break; if (_sp > XB_SPIN_CAP) { atomicAdd(&(bar)[XB_TMO], 1u); break; } } } } while (0)
; __device__ __forceinline__ void m2_phase(const Params& p, unsigned char* ldsg, int G) {
;     const int tid = threadIdx.x, lane = tid & 63, wave = __builtin_amdgcn_readfirstlane(tid >> 6);
;     unsigned char* ws = p.ws;
;     bf16* DCB = (bf16*)p.out; float* DN = (float*)(ws + WS_DN); const float* GARR = (const float*)(ws + WS_SC); const float* AMAXARR = GARR + 1024; float* MPREV = (float*)(ws + WS_SC) + 2048;
;     float* sA = (float*)ldsg; float* sB = sA + 256; float* sAseg = sA + 512; float* sTot = sA + 1024;
;     for (int it = blockIdx.x; it < 256; it += G) {
;         const int h = it >> 6, slice = it & 63, c0 = 32 * wave;
;         u32x2 x[32];
;         char* ub = (char*)DCB + (((size_t)((h * 64 + slice) * NCH + c0) << 8) * 2);
;         const unsigned loff = (unsigned)lane * 8u;
; #pragma unroll
;         for (int i = 0; i < 32; ++i) x[i] = *(const u32x2*)(ub + (size_t)i * 512 + loff);
; __device__ __forceinline__ void xcd_barrier(const XcdBarrier& b) {
;     ...
;         const unsigned old = xb_add(&bar[XB_XSUB(b.x)], 1u);
;         const unsigned gen = old / nloc;
;         if (old + 1u == (gen + 1u) * nloc) {
;             __builtin_amdgcn_fence(__ATOMIC_RELEASE, "agent");
;             asm volatile("s_waitcnt vmcnt(0)" ::: "memory");
;             const unsigned og = xb_add(&bar[XB_TOP], 1u);
;             const unsigned tg = og / nx;
;             if (og + 1u == (tg + 1u) * nx) xb_add(&bar[XB_TOPGEN], 1u);
;             else XB_SPIN(xb_ld(&bar[XB_TOPGEN]) == tg, bar);
;             __builtin_amdgcn_fence(__ATOMIC_ACQUIRE, "agent");
;             xb_add(&bar[XB_XGEN(b.x)], 1u);
;             asm volatile("s_waitcnt vmcnt(0)" ::: "memory");
; __global__ void __launch_bounds__(512, 2) fwd_megakernel(Params p) {
;     ...
;     m2_phase(p, lds, G);
.LBB0_1028:
.LBB0_1029:
	s_or_b64 exec, exec, s[0:1]
	v_readlane_b32 s4, v255, 12
	s_add_u32 s0, s72, 0x502000
	v_readlane_b32 s5, v255, 13
	v_readfirstlane_b32 s2, v152
	s_addc_u32 s1, s73, 0
	s_and_b64 vcc, exec, s[4:5]
	v_lshlrev_b32_e32 v48, 2, v153
	s_waitcnt lgkmcnt(0)
	s_barrier
	s_cbranch_vccnz .LBB0_1062
	s_lshr_b32 s6, s2, 6
	s_lshl_b32 s3, s6, 5
	s_cmp_lt_u32 s2, 64
	s_cselect_b64 s[22:23], -1, 0
	s_cmp_gt_u32 s2, 63
	s_cselect_b64 s[24:25], -1, 0
	s_lshl_b32 s4, s6, 10
	v_mov_b32_e32 v32, 0
	s_add_i32 s4, s4, 0
	s_mul_i32 s5, s6, 0xfffffc04
	v_mov_b32_e32 v95, v32
	v_add_u32_e32 v49, s4, v174
	s_add_i32 s49, s4, s5
	s_mul_i32 s4, s6, 0x7c
	s_add_i32 s33, s49, s4
	v_lshl_add_u64 v[0:1], s[72:73], 0, v[94:95]
	s_mov_b64 s[4:5], 0x480000
	v_lshl_add_u64 v[40:41], v[0:1], 0, s[4:5]
	s_add_i32 s4, s6, -1
	s_bfe_u32 s2, s2, 0x30006
	v_mov_b32_e32 v175, v32
	s_cmp_gt_u32 s4, 6
	v_writelane_b32 v255, s96, 14
	v_lshl_add_u64 v[34:35], s[34:35], 0, v[174:175]
	s_cselect_b64 s[26:27], -1, 0
	s_and_b32 s34, s6, 0x3fffff8
	v_writelane_b32 v255, s97, 15
	v_add_u32_e32 v2, 0, v174
	s_cmp_lg_u32 s2, 0
	v_add_u32_e32 v0, 0, v94
	v_sub_u32_e32 v3, 0, v94
	v_sub_u32_e32 v4, v2, v94
	v_writelane_b32 v255, s2, 11
	s_cselect_b64 s[28:29], -1, 0
	v_add_u32_e32 v161, 0x1000, v0
	s_add_i32 s2, 0, 0x800
	v_mbcnt_lo_u32_b32 v0, -1, 0
	v_lshl_add_u64 v[36:37], s[36:37], 0, v[174:175]
	v_cmp_eq_u32_e64 s[8:9], 0, v153
	v_cmp_gt_u32_e64 s[10:11], 2, v153
	v_cmp_gt_u32_e64 s[12:13], 4, v153
	v_cmp_gt_u32_e64 s[14:15], 8, v153
	v_cmp_gt_u32_e64 s[16:17], 16, v153
	v_cmp_gt_u32_e64 s[18:19], 32, v153
	v_lshl_add_u64 v[38:39], s[70:71], 0, v[94:95]
	s_movk_i32 s46, 0x1000
	v_add_u32_e32 v93, 0x1000, v2
	s_mov_b64 s[50:51], 0x1c00
	s_mov_b64 s[58:59], 0x1e00
	s_mov_b64 s[60:61], 0x2000
	s_movk_i32 s35, 0x2000
	s_mov_b64 s[62:63], 0x2200
	s_mov_b64 s[64:65], 0x2400
	s_mov_b64 s[80:81], 0x2600
	s_mov_b64 s[82:83], 0x2800
	s_mov_b64 s[84:85], 0x2a00
	s_mov_b64 s[40:41], 0x2c00
	s_mov_b64 s[88:89], 0x2e00
	s_mov_b64 s[90:91], 0x3000
	s_mov_b64 s[92:93], 0x3200
	s_mov_b64 s[94:95], 0x3400
	s_mov_b64 s[96:97], 0x3600
	s_mov_b64 s[4:5], 0x3800
	s_mov_b64 s[44:45], 0x3a00
	s_mov_b32 s36, 0x3fb8aa3b
	s_mov_b32 s37, 0xc2ce8ed0
	s_mov_b32 s38, 0x42b17218
	v_writelane_b32 v255, s2, 16
	s_movk_i32 s39, 0x7fff
	v_add_u32_e32 v163, v49, v3
	v_mbcnt_hi_u32_b32 v169, -1, v0
	v_mov_b32_e32 v171, 0x7f800000
	v_add_u32_e32 v248, v4, v94
	v_mov_b32_e32 v249, 1
	s_mov_b32 s2, s86
	s_mov_b64 s[6:7], 0x3c00
	s_mov_b64 s[42:43], 0x3e00
	s_branch .LBB0_1033

; __device__ __forceinline__ unsigned xb_ld(unsigned* p)              { return __hip_atomic_load(p, __ATOMIC_RELAXED, __HIP_MEMORY_SCOPE_AGENT); }
; __device__ __forceinline__ unsigned xb_add(unsigned* p, unsigned v) { return __hip_atomic_fetch_add(p, v, __ATOMIC_RELAXED, __HIP_MEMORY_SCOPE_AGENT); }
; #define XB_SPIN(cond, bar) do { unsigned _sp = 0; while (cond) { __builtin_amdgcn_s_sleep(1); \
;     if ((++_sp & 255u) == 0u) { if (xb_ld(&(bar)[XB_TMO])) break; if (_sp > XB_SPIN_CAP) { atomicAdd(&(bar)[XB_TMO], 1u); break; } } } } while (0)
; __device__ __forceinline__ void m3_phase(const Params& p, unsigned char* ldsg, int G) {
;     ...
;     if ((int)blockIdx.x < NCH * NH) M3_ISSUE((int)blockIdx.x);
; __device__ __forceinline__ void xcd_barrier(const XcdBarrier& b) {
;     ...
;         const unsigned old = xb_add(&bar[XB_XSUB(b.x)], 1u);
;         const unsigned gen = old / nloc;
;         if (old + 1u == (gen + 1u) * nloc) {
;             __builtin_amdgcn_fence(__ATOMIC_RELEASE, "agent");
;             asm volatile("s_waitcnt vmcnt(0)" ::: "memory");
;             const unsigned og = xb_add(&bar[XB_TOP], 1u);
;             const unsigned tg = og / nx;
;             if (og + 1u == (tg + 1u) * nx) xb_add(&bar[XB_TOPGEN], 1u);
;             else XB_SPIN(xb_ld(&bar[XB_TOPGEN]) == tg, bar);
;             __builtin_amdgcn_fence(__ATOMIC_ACQUIRE, "agent");
;             xb_add(&bar[XB_XGEN(b.x)], 1u);
;             asm volatile("s_waitcnt vmcnt(0)" ::: "memory");
; __global__ void __launch_bounds__(512, 2) fwd_megakernel(Params p) {
;     ...
;     m3_phase(p, lds, G);
.LBB0_1113:
.LBB0_1114:
	s_or_b64 exec, exec, s[4:5]
	s_add_u32 s20, s72, 0x480000
	s_addc_u32 s21, s73, 0
	s_cmpk_lt_i32 s86, 0x400
	s_cselect_b64 s[4:5], -1, 0
	s_cmpk_gt_i32 s86, 0x3ff
	v_readfirstlane_b32 s3, v152
	s_waitcnt lgkmcnt(0)
	s_barrier
	s_cbranch_scc1 .LBB0_1116
	s_ashr_i32 s2, s86, 2
	s_lshl_b32 s11, s2, 6
	v_or_b32_e32 v16, s11, v165
	v_ashrrev_i32_e32 v17, 31, v16
	s_and_b32 s10, s86, 3
	v_lshlrev_b64 v[0:1], 11, v[16:17]
	v_lshl_add_u64 v[0:1], s[56:57], 0, v[0:1]
	s_lshl_b32 s6, s10, 8
	s_mov_b32 s7, 0
	v_lshl_add_u64 v[0:1], v[0:1], 0, s[6:7]
	v_and_b32_e32 v50, 0xf0, v247
	v_mov_b32_e32 v51, 0
	v_lshl_add_u64 v[4:5], v[0:1], 0, v[50:51]
	s_movk_i32 s12, 0x1600
	v_mov_b64_e32 v[18:19], s[78:79]
	global_load_dwordx4 v[8:11], v[4:5], off
	global_load_dwordx4 v[0:3], v[4:5], off offset:1024
	v_mad_i64_i32 v[4:5], s[8:9], v16, s12, v[18:19]
	v_add_u32_e32 v16, 32, v16
	v_ashrrev_i32_e32 v17, 31, v16
	v_lshlrev_b64 v[20:21], 11, v[16:17]
	v_lshl_add_u64 v[20:21], s[56:57], 0, v[20:21]
	v_mad_i64_i32 v[16:17], s[8:9], v16, s12, v[18:19]
	v_lshl_add_u64 v[4:5], v[4:5], 0, s[6:7]
	v_lshl_add_u64 v[20:21], v[20:21], 0, s[6:7]
	v_lshl_add_u64 v[16:17], v[16:17], 0, s[6:7]
	s_lshl_b32 s6, s10, 14
	s_add_i32 s2, s6, s2
	v_and_b32_e32 v32, 0x1f00, v230
	v_add_u32_e32 v42, s2, v32
	v_lshl_add_u64 v[12:13], v[4:5], 0, v[50:51]
	v_lshl_add_u64 v[28:29], v[20:21], 0, v[50:51]
	v_ashrrev_i32_e32 v43, 31, v42
	global_load_dwordx4 v[4:7], v[12:13], off offset:2048
	s_nop 0
	global_load_dwordx4 v[12:15], v[12:13], off offset:3072
	s_nop 0
	global_load_dwordx4 v[24:27], v[28:29], off
	global_load_dwordx4 v[20:23], v[28:29], off offset:1024
	v_lshl_add_u64 v[28:29], v[16:17], 0, v[50:51]
	v_and_b32_e32 v50, 0x1f0, v247
	v_lshlrev_b64 v[32:33], 9, v[42:43]
	v_add_u32_e32 v42, 0x2000, v42
	v_lshl_add_u64 v[40:41], s[70:71], 0, v[50:51]
	v_ashrrev_i32_e32 v43, 31, v42
	v_lshl_add_u64 v[44:45], v[40:41], 0, v[32:33]
	v_add_u32_e32 v32, 0x1000, v230
	v_lshlrev_b64 v[42:43], 9, v[42:43]
	v_and_b32_e32 v32, 0x3f00, v32
	v_lshl_add_u64 v[52:53], v[40:41], 0, v[42:43]
	v_add_u32_e32 v42, 0x3000, v230
	v_add_u32_e32 v32, s2, v32
	v_and_b32_e32 v42, 0x7f00, v42
	v_ashrrev_i32_e32 v33, 31, v32
	v_add_u32_e32 v42, s2, v42
	v_lshlrev_b64 v[32:33], 9, v[32:33]
	v_ashrrev_i32_e32 v43, 31, v42
	v_lshl_add_u64 v[46:47], v[40:41], 0, v[32:33]
	v_lshlrev_b64 v[42:43], 9, v[42:43]
	global_load_dwordx4 v[16:19], v[28:29], off offset:2048
	s_nop 0
	global_load_dwordx4 v[28:31], v[28:29], off offset:3072
	s_nop 0
	global_load_dwordx4 v[32:35], v[44:45], off
	global_load_dwordx4 v[36:39], v[46:47], off
	v_lshl_add_u64 v[54:55], v[40:41], 0, v[42:43]
	global_load_dwordx4 v[40:43], v[52:53], off
	global_load_dwordx4 v[44:47], v[54:55], off
	v_or_b32_e32 v52, s11, v153
	v_ashrrev_i32_e32 v53, 31, v52
	v_lshlrev_b64 v[52:53], 5, v[52:53]
	v_lshl_add_u64 v[52:53], s[54:55], 0, v[52:53]
	s_lshl_b32 s6, s10, 2
	s_mulk_i32 s10, 0xc100
	v_lshl_add_u64 v[52:53], v[52:53], 0, s[6:7]
	s_add_i32 s6, s2, s10
	s_ashr_i32 s7, s6, 31
	s_lshl_b64 s[8:9], s[6:7], 2
	s_add_u32 s8, s0, s8
	s_addc_u32 s9, s1, s9
	s_lshl_b64 s[6:7], s[6:7], 9
	s_add_u32 s6, s20, s6
	s_addc_u32 s7, s21, s7
	global_load_dword v130, v[52:53], off
	global_load_dword v193, v[52:53], off offset:16
	global_load_dword v111, v51, s[8:9]
	global_load_dword v195, v48, s[6:7]
	global_load_dword v194, v48, s[6:7] offset:256
	s_add_u32 s48, s72, 0x8800000
	s_addc_u32 s49, s73, 0
	s_andn2_b64 vcc, exec, s[4:5]
	s_cbranch_vccz .LBB0_1117
	s_branch .LBB0_1159

; __device__ __forceinline__ unsigned xb_ld(unsigned* p)              { return __hip_atomic_load(p, __ATOMIC_RELAXED, __HIP_MEMORY_SCOPE_AGENT); }
; __device__ __forceinline__ unsigned xb_add(unsigned* p, unsigned v) { return __hip_atomic_fetch_add(p, v, __ATOMIC_RELAXED, __HIP_MEMORY_SCOPE_AGENT); }
; #define XB_SPIN(cond, bar) do { unsigned _sp = 0; while (cond) { __builtin_amdgcn_s_sleep(1); \
;     if ((++_sp & 255u) == 0u) { if (xb_ld(&(bar)[XB_TMO])) break; if (_sp > XB_SPIN_CAP) { atomicAdd(&(bar)[XB_TMO], 1u); break; } } } } while (0)
; #define GSYNC() xcd_barrier(xb)
;     __host__ __device__ bool next(int i, Unit& u) const {
;         const long L = (long)i * G + c; if (L >= nwg) return false;
;         int wgid = (int)L; { const int q = nwg / NXCD, r = nwg % NXCD, xcd = wgid % NXCD, off = wgid / NXCD; wgid = (xcd < r ? xcd * (q + 1) : r * (q + 1) + (xcd - r) * q) + off; }
;         const int nig = WGM * nN, gid = wgid / nig, fm = gid * WGM, gsz = (nM - fm) < WGM ? (nM - fm) : WGM;
;         u.pm = fm + ((wgid % nig) % gsz); u.pn = (wgid % nig) / gsz; return true;
; __device__ __forceinline__ void xcd_barrier(const XcdBarrier& b) {
;     ...
;         const unsigned old = xb_add(&bar[XB_XSUB(b.x)], 1u);
;         const unsigned gen = old / nloc;
;         if (old + 1u == (gen + 1u) * nloc) {
;             __builtin_amdgcn_fence(__ATOMIC_RELEASE, "agent");
;             asm volatile("s_waitcnt vmcnt(0)" ::: "memory");
;             const unsigned og = xb_add(&bar[XB_TOP], 1u);
;             const unsigned tg = og / nx;
;             if (og + 1u == (tg + 1u) * nx) xb_add(&bar[XB_TOPGEN], 1u);
;             else XB_SPIN(xb_ld(&bar[XB_TOPGEN]) == tg, bar);
;             __builtin_amdgcn_fence(__ATOMIC_ACQUIRE, "agent");
;             xb_add(&bar[XB_XGEN(b.x)], 1u);
;             asm volatile("s_waitcnt vmcnt(0)" ::: "memory");
; __global__ void __launch_bounds__(512, 2) fwd_megakernel(Params p) {
;     ...
;     GSYNC();
;     { pg8::Gemm g{MIX, (const bf16*)(ws + WS_WOUT), S, DM, DM}; pg8::StaticOrder so; so.init(S, DM, G, (int)blockIdx.x);
;       pg8::EpiResid<true> E{nullptr, XB, SS2, 1.0f}; pg8::gemm_phase<pg8::EpiResid<true>, pg8::StaticOrder, true, true>(ldsl, g, so, E); }
.LBB0_1210:
.LBB0_1211:
	s_or_b64 exec, exec, s[0:1]
	v_readlane_b32 s0, v255, 12
	v_readlane_b32 s1, v255, 13
	s_and_b64 vcc, exec, s[0:1]
	v_readfirstlane_b32 s8, v152
	s_waitcnt lgkmcnt(0)
	s_barrier
	s_cbranch_vccnz .LBB0_1217
	s_ashr_i32 s0, s86, 31
	s_lshr_b32 s0, s0, 29
	s_add_i32 s2, s86, s0
	s_and_b32 s0, s2, -8
	s_sub_i32 s3, s86, s0
	s_cmp_gt_i32 s3, -1
	s_cbranch_scc0 .LBB0_1214
	s_lshl_b32 s4, s3, 5
	s_cbranch_execz .LBB0_1215
	s_branch .LBB0_1216

; __device__ __forceinline__ unsigned xb_ld(unsigned* p)              { return __hip_atomic_load(p, __ATOMIC_RELAXED, __HIP_MEMORY_SCOPE_AGENT); }
; __device__ __forceinline__ unsigned xb_add(unsigned* p, unsigned v) { return __hip_atomic_fetch_add(p, v, __ATOMIC_RELAXED, __HIP_MEMORY_SCOPE_AGENT); }
; #define XB_SPIN(cond, bar) do { unsigned _sp = 0; while (cond) { __builtin_amdgcn_s_sleep(1); \
;     if ((++_sp & 255u) == 0u) { if (xb_ld(&(bar)[XB_TMO])) break; if (_sp > XB_SPIN_CAP) { atomicAdd(&(bar)[XB_TMO], 1u); break; } } } } while (0)
; #define GSYNC() xcd_barrier(xb)
;     __host__ __device__ bool next(int i, Unit& u) const {
;         const long L = (long)i * G + c; if (L >= nwg) return false;
;         int wgid = (int)L; { const int q = nwg / NXCD, r = nwg % NXCD, xcd = wgid % NXCD, off = wgid / NXCD; wgid = (xcd < r ? xcd * (q + 1) : r * (q + 1) + (xcd - r) * q) + off; }
;         const int nig = WGM * nN, gid = wgid / nig, fm = gid * WGM, gsz = (nM - fm) < WGM ? (nM - fm) : WGM;
;         u.pm = fm + ((wgid % nig) % gsz); u.pn = (wgid % nig) / gsz; return true;
; __device__ __forceinline__ void xcd_barrier(const XcdBarrier& b) {
;     ...
;         const unsigned old = xb_add(&bar[XB_XSUB(b.x)], 1u);
;         const unsigned gen = old / nloc;
;         if (old + 1u == (gen + 1u) * nloc) {
;             __builtin_amdgcn_fence(__ATOMIC_RELEASE, "agent");
;             asm volatile("s_waitcnt vmcnt(0)" ::: "memory");
;             const unsigned og = xb_add(&bar[XB_TOP], 1u);
;             const unsigned tg = og / nx;
;             if (og + 1u == (tg + 1u) * nx) xb_add(&bar[XB_TOPGEN], 1u);
;             else XB_SPIN(xb_ld(&bar[XB_TOPGEN]) == tg, bar);
;             __builtin_amdgcn_fence(__ATOMIC_ACQUIRE, "agent");
;             xb_add(&bar[XB_XGEN(b.x)], 1u);
;             asm volatile("s_waitcnt vmcnt(0)" ::: "memory");
; __global__ void __launch_bounds__(512, 2) fwd_megakernel(Params p) {
;     ...
;     GSYNC();
;     { pg8::Gemm g{XB, (const bf16*)(ws + WS_WGU2), S, 2 * DFF, DM}; pg8::StaticOrder so; so.init(S, 2 * DFF, G, (int)blockIdx.x);
;       const int pm0 = fill_rtab(so, SS2, rtab); pg8::EpiSwiGLU E{HB, DFF, SS2, rtab, pm0}; pg8::gemm_phase<pg8::EpiSwiGLU, pg8::StaticOrder, true, true>(ldsl, g, so, E); }
.LBB0_1304:
.LBB0_1305:
	s_or_b64 exec, exec, s[0:1]
	s_and_b64 vcc, exec, s[48:49]
	s_waitcnt lgkmcnt(0)
	s_barrier
	s_cbranch_vccnz .LBB0_1307
	s_ashr_i32 s0, s86, 31
	s_lshr_b32 s0, s0, 29
	s_add_i32 s0, s86, s0
	s_ashr_i32 s1, s0, 3
	s_and_b32 s0, s0, -8
	s_sub_i32 s0, s86, s0
	s_cmp_lt_i32 s0, 0
	s_movk_i32 s2, 0xb1
	s_cselect_b32 s2, s2, 0xb0
	s_mul_i32 s0, s0, s2
	s_add_i32 s0, s0, s1
	s_mul_hi_i32 s1, s0, 0x2e8ba2e9
	s_lshr_b32 s2, s1, 31
	s_ashr_i32 s1, s1, 5
	s_add_i32 s1, s1, s2
	s_lshl_b32 s2, s1, 3
	s_mulk_i32 s1, 0xb0
	s_sub_i32 s0, s0, s1
	s_bfe_u32 s1, s0, 0x3001c
	s_add_i32 s1, s0, s1
	s_and_b32 s1, s1, 0xfff8
	s_sub_i32 s0, s0, s1
	s_sext_i32_i16 s0, s0
	s_add_i32 s3, s2, s0

; __device__ __forceinline__ unsigned xb_ld(unsigned* p)              { return __hip_atomic_load(p, __ATOMIC_RELAXED, __HIP_MEMORY_SCOPE_AGENT); }
; __device__ __forceinline__ unsigned xb_add(unsigned* p, unsigned v) { return __hip_atomic_fetch_add(p, v, __ATOMIC_RELAXED, __HIP_MEMORY_SCOPE_AGENT); }
; #define XB_SPIN(cond, bar) do { unsigned _sp = 0; while (cond) { __builtin_amdgcn_s_sleep(1); \
;     if ((++_sp & 255u) == 0u) { if (xb_ld(&(bar)[XB_TMO])) break; if (_sp > XB_SPIN_CAP) { atomicAdd(&(bar)[XB_TMO], 1u); break; } } } } while (0)
; #define GSYNC() xcd_barrier(xb)
;     __host__ __device__ bool next(int i, Unit& u) const {
;         const long L = (long)i * G + c; if (L >= nwg) return false;
;         int wgid = (int)L; { const int q = nwg / NXCD, r = nwg % NXCD, xcd = wgid % NXCD, off = wgid / NXCD; wgid = (xcd < r ? xcd * (q + 1) : r * (q + 1) + (xcd - r) * q) + off; }
;         const int nig = WGM * nN, gid = wgid / nig, fm = gid * WGM, gsz = (nM - fm) < WGM ? (nM - fm) : WGM;
;         u.pm = fm + ((wgid % nig) % gsz); u.pn = (wgid % nig) / gsz; return true;
; __device__ __forceinline__ void xcd_barrier(const XcdBarrier& b) {
;     ...
;         const unsigned old = xb_add(&bar[XB_XSUB(b.x)], 1u);
;         const unsigned gen = old / nloc;
;         if (old + 1u == (gen + 1u) * nloc) {
;             __builtin_amdgcn_fence(__ATOMIC_RELEASE, "agent");
;             asm volatile("s_waitcnt vmcnt(0)" ::: "memory");
;             const unsigned og = xb_add(&bar[XB_TOP], 1u);
;             const unsigned tg = og / nx;
;             if (og + 1u == (tg + 1u) * nx) xb_add(&bar[XB_TOPGEN], 1u);
;             else XB_SPIN(xb_ld(&bar[XB_TOPGEN]) == tg, bar);
;             __builtin_amdgcn_fence(__ATOMIC_ACQUIRE, "agent");
;             xb_add(&bar[XB_XGEN(b.x)], 1u);
;             asm volatile("s_waitcnt vmcnt(0)" ::: "memory");
; __global__ void __launch_bounds__(512, 2) fwd_megakernel(Params p) {
;     ...
;     GSYNC();
;     { pg8::Gemm g{HB, (const bf16*)(ws + WS_WD2), S, DM, DFF}; pg8::StaticOrder so; so.init(S, DM, G, (int)blockIdx.x);
;       pg8::EpiFinal E{XB, p.out, SS3, (unsigned*)(ws + WS_PCNT), p.nf, 0.5f}; pg8::gemm_phase<pg8::EpiFinal, pg8::StaticOrder, true, true>(ldsl, g, so, E); }
.LBB0_1418:
.LBB0_1419:
	s_or_b64 exec, exec, s[0:1]
	v_readlane_b32 s0, v255, 12
	v_readlane_b32 s1, v255, 13
	s_and_b64 vcc, exec, s[0:1]
	v_readfirstlane_b32 s4, v152
	s_waitcnt lgkmcnt(0)
	s_barrier
	s_cbranch_vccnz .LBB0_1425
	s_ashr_i32 s0, s86, 31
	s_lshr_b32 s0, s0, 29
	s_add_i32 s5, s86, s0
	s_and_b32 s0, s5, -8
	s_sub_i32 s2, s86, s0
	s_cmp_gt_i32 s2, -1
	s_cbranch_scc0 .LBB0_1422
	s_lshl_b32 s3, s2, 5
	s_ashr_i32 s0, s5, 3
	s_cbranch_execz .LBB0_1423
	s_branch .LBB0_1424
